# attention item: short-conv rewritten with all 28 row loads issued up front and counted waits (was serial load-wait chains per token row)
# speedup vs baseline: 1.0244x; 1.0040x over previous
.LBB0_96:
	s_lshl_b32 s23, s38, 11
	s_and_b32 s22, s39, s37
	s_addk_i32 s23, 0x2000
	s_lshl_b32 s24, s38, 8
	s_and_b64 s[12:13], s[12:13], exec
	s_cselect_b32 s24, s23, s24
	s_lshl_b32 s25, s22, 7
	s_waitcnt lgkmcnt(0)
	s_add_u32 s12, s4, s29
	s_addc_u32 s13, s5, 0
	s_add_u32 s22, s12, 0x629c000
	s_addc_u32 s23, s13, 0
	global_load_dword v113, v192, s[12:13]
	global_load_dword v112, v133, s[22:23] offset:8
	s_mov_b64 s[12:13], s[0:1]
	s_load_dwordx2 s[12:13], s[12:13], 0x68
	v_lshlrev_b32_e32 v0, 2, v40
	v_and_b32_e32 v0, 60, v0
	v_ashrrev_i32_e32 v13, 4, v40
	v_lshl_or_b32 v12, s35, 6, v0
	v_add_u32_e32 v29, s25, v13
	v_lshlrev_b32_e32 v0, 2, v12
	v_lshlrev_b32_e32 v132, 1, v12
	v_add_u32_e32 v18, s24, v29
	v_ashrrev_i32_e32 v19, 31, v18
	s_waitcnt lgkmcnt(0)
	s_add_u32 s12, s12, s6
	s_addc_u32 s13, s13, s7
	global_load_dwordx4 v[8:11], v0, s[12:13]
	global_load_dwordx4 v[4:7], v0, s[12:13] offset:1024
	s_nop 0
	global_load_dwordx4 v[0:3], v0, s[12:13] offset:2048
	v_lshl_add_u64 v[14:15], s[4:5], 0, v[132:133]
	v_lshlrev_b64 v[20:21], 9, v[18:19]
	s_mov_b64 s[12:13], 0xdea4400
	v_lshl_add_u64 v[16:17], v[14:15], 0, s[12:13]
	s_mov_b64 s[12:13], 0xe6a4400
	v_lshl_add_u64 v[22:23], v[14:15], 0, s[12:13]
	s_mov_b64 s[12:13], 0xd6a4400
	v_lshl_add_u64 v[24:25], v[14:15], 0, s[12:13]
	v_lshl_add_u64 v[16:17], v[16:17], 0, v[20:21]
	v_lshl_add_u64 v[22:23], v[22:23], 0, v[20:21]
	v_lshl_add_u64 v[24:25], v[24:25], 0, v[20:21]
	global_load_dwordx2 v[44:45], v[16:17], off offset:-512
	global_load_dwordx2 v[46:47], v[16:17], off
	global_load_dwordx2 v[48:49], v[16:17], off offset:512
	global_load_dwordx2 v[50:51], v[22:23], off offset:-512
	global_load_dwordx2 v[52:53], v[22:23], off
	global_load_dwordx2 v[54:55], v[22:23], off offset:512
	global_load_dwordx2 v[56:57], v[24:25], off
	v_lshl_add_u64 v[16:17], v[16:17], 0, s[76:77]
	v_lshl_add_u64 v[22:23], v[22:23], 0, s[76:77]
	v_lshl_add_u64 v[24:25], v[24:25], 0, s[76:77]
	global_load_dwordx2 v[58:59], v[16:17], off offset:-512
	global_load_dwordx2 v[60:61], v[16:17], off
	global_load_dwordx2 v[62:63], v[16:17], off offset:512
	global_load_dwordx2 v[64:65], v[22:23], off offset:-512
	global_load_dwordx2 v[66:67], v[22:23], off
	global_load_dwordx2 v[68:69], v[22:23], off offset:512
	global_load_dwordx2 v[70:71], v[24:25], off
	v_lshl_add_u64 v[16:17], v[16:17], 0, s[76:77]
	v_lshl_add_u64 v[22:23], v[22:23], 0, s[76:77]
	v_lshl_add_u64 v[24:25], v[24:25], 0, s[76:77]
	global_load_dwordx2 v[72:73], v[16:17], off offset:-512
	global_load_dwordx2 v[74:75], v[16:17], off
	global_load_dwordx2 v[76:77], v[16:17], off offset:512
	global_load_dwordx2 v[78:79], v[22:23], off offset:-512
	global_load_dwordx2 v[80:81], v[22:23], off
	global_load_dwordx2 v[82:83], v[22:23], off offset:512
	global_load_dwordx2 v[84:85], v[24:25], off
	v_lshl_add_u64 v[16:17], v[16:17], 0, s[76:77]
	v_lshl_add_u64 v[22:23], v[22:23], 0, s[76:77]
	v_lshl_add_u64 v[24:25], v[24:25], 0, s[76:77]
	global_load_dwordx2 v[86:87], v[16:17], off offset:-512
	global_load_dwordx2 v[88:89], v[16:17], off
	global_load_dwordx2 v[90:91], v[16:17], off offset:512
	global_load_dwordx2 v[92:93], v[22:23], off offset:-512
	global_load_dwordx2 v[94:95], v[22:23], off
	global_load_dwordx2 v[96:97], v[22:23], off offset:512
	global_load_dwordx2 v[98:99], v[24:25], off
	s_add_u32 s12, s4, 0xfea4400
	s_addc_u32 s13, s5, 0
	v_mov_b64_e32 v[26:27], s[12:13]
	v_mad_i64_i32 v[26:27], s[22:23], v18, s96, v[26:27]
	v_lshl_add_u64 v[26:27], v[26:27], 0, v[132:133]
	s_mov_b64 s[12:13], 0x14000
	v_add_u32_e32 v28, 0x60, v29
	s_waitcnt vmcnt(21)
	v_lshlrev_b32_e32 v100, 16, v44
	v_and_b32_e32 v101, 0xffff0000, v44
	v_lshlrev_b32_e32 v102, 16, v50
	v_and_b32_e32 v103, 0xffff0000, v50
	v_lshlrev_b32_e32 v104, 16, v45
	v_and_b32_e32 v105, 0xffff0000, v45
	v_lshlrev_b32_e32 v106, 16, v51
	v_and_b32_e32 v107, 0xffff0000, v51
	v_pk_mul_f32 v[30:31], v[100:101], v[102:103]
	v_pk_mul_f32 v[32:33], v[104:105], v[106:107]
	v_lshlrev_b32_e32 v100, 16, v46
	v_and_b32_e32 v101, 0xffff0000, v46
	v_lshlrev_b32_e32 v102, 16, v52
	v_and_b32_e32 v103, 0xffff0000, v52
	v_lshlrev_b32_e32 v104, 16, v47
	v_and_b32_e32 v105, 0xffff0000, v47
	v_lshlrev_b32_e32 v106, 16, v53
	v_and_b32_e32 v107, 0xffff0000, v53
	v_pk_mul_f32 v[34:35], v[100:101], v[102:103]
	v_pk_mul_f32 v[36:37], v[104:105], v[106:107]
	v_lshlrev_b32_e32 v100, 16, v48
	v_and_b32_e32 v101, 0xffff0000, v48
	v_lshlrev_b32_e32 v102, 16, v54
	v_and_b32_e32 v103, 0xffff0000, v54
	v_lshlrev_b32_e32 v104, 16, v49
	v_and_b32_e32 v105, 0xffff0000, v49
	v_lshlrev_b32_e32 v106, 16, v55
	v_and_b32_e32 v107, 0xffff0000, v55
	v_pk_mul_f32 v[108:109], v[100:101], v[102:103]
	v_pk_mul_f32 v[110:111], v[104:105], v[106:107]
	v_cmp_lt_i32_e32 vcc, 0, v29
	s_nop 1
	v_cndmask_b32_e32 v30, 0, v30, vcc
	v_cndmask_b32_e32 v31, 0, v31, vcc
	v_cndmask_b32_e32 v32, 0, v32, vcc
	v_cndmask_b32_e32 v33, 0, v33, vcc
	v_pk_mul_f32 v[32:33], v[10:11], v[32:33]
	v_pk_mul_f32 v[30:31], v[8:9], v[30:31]
	v_pk_fma_f32 v[32:33], v[6:7], v[36:37], v[32:33]
	v_pk_fma_f32 v[30:31], v[4:5], v[34:35], v[30:31]
	v_pk_fma_f32 v[30:31], v[0:1], v[108:109], v[30:31]
	v_pk_fma_f32 v[32:33], v[2:3], v[110:111], v[32:33]
	v_lshlrev_b32_e32 v100, 16, v56
	v_and_b32_e32 v101, 0xffff0000, v56
	v_lshlrev_b32_e32 v102, 16, v57
	v_and_b32_e32 v103, 0xffff0000, v57
	v_pk_mul_f32 v[32:33], v[32:33], v[102:103]
	v_pk_mul_f32 v[30:31], v[30:31], v[100:101]
	v_cvt_pk_bf16_f32 v30, v30, v31
	v_cvt_pk_bf16_f32 v31, v32, v33
	global_store_dwordx2 v[26:27], v[30:31], off offset:1024
	v_lshl_add_u64 v[26:27], v[26:27], 0, s[12:13]
	s_waitcnt vmcnt(14)
	v_lshlrev_b32_e32 v100, 16, v58
	v_and_b32_e32 v101, 0xffff0000, v58
	v_lshlrev_b32_e32 v102, 16, v64
	v_and_b32_e32 v103, 0xffff0000, v64
	v_lshlrev_b32_e32 v104, 16, v59
	v_and_b32_e32 v105, 0xffff0000, v59
	v_lshlrev_b32_e32 v106, 16, v65
	v_and_b32_e32 v107, 0xffff0000, v65
	v_pk_mul_f32 v[30:31], v[100:101], v[102:103]
	v_pk_mul_f32 v[32:33], v[104:105], v[106:107]
	v_lshlrev_b32_e32 v100, 16, v60
	v_and_b32_e32 v101, 0xffff0000, v60
	v_lshlrev_b32_e32 v102, 16, v66
	v_and_b32_e32 v103, 0xffff0000, v66
	v_lshlrev_b32_e32 v104, 16, v61
	v_and_b32_e32 v105, 0xffff0000, v61
	v_lshlrev_b32_e32 v106, 16, v67
	v_and_b32_e32 v107, 0xffff0000, v67
	v_pk_mul_f32 v[34:35], v[100:101], v[102:103]
	v_pk_mul_f32 v[36:37], v[104:105], v[106:107]
	v_lshlrev_b32_e32 v100, 16, v62
	v_and_b32_e32 v101, 0xffff0000, v62
	v_lshlrev_b32_e32 v102, 16, v68
	v_and_b32_e32 v103, 0xffff0000, v68
	v_lshlrev_b32_e32 v104, 16, v63
	v_and_b32_e32 v105, 0xffff0000, v63
	v_lshlrev_b32_e32 v106, 16, v69
	v_and_b32_e32 v107, 0xffff0000, v69
	v_pk_mul_f32 v[108:109], v[100:101], v[102:103]
	v_pk_mul_f32 v[110:111], v[104:105], v[106:107]
	v_pk_mul_f32 v[32:33], v[10:11], v[32:33]
	v_pk_mul_f32 v[30:31], v[8:9], v[30:31]
	v_pk_fma_f32 v[32:33], v[6:7], v[36:37], v[32:33]
	v_pk_fma_f32 v[30:31], v[4:5], v[34:35], v[30:31]
	v_pk_fma_f32 v[30:31], v[0:1], v[108:109], v[30:31]
	v_pk_fma_f32 v[32:33], v[2:3], v[110:111], v[32:33]
	v_lshlrev_b32_e32 v100, 16, v70
	v_and_b32_e32 v101, 0xffff0000, v70
	v_lshlrev_b32_e32 v102, 16, v71
	v_and_b32_e32 v103, 0xffff0000, v71
	v_pk_mul_f32 v[32:33], v[32:33], v[102:103]
	v_pk_mul_f32 v[30:31], v[30:31], v[100:101]
	v_cvt_pk_bf16_f32 v30, v30, v31
	v_cvt_pk_bf16_f32 v31, v32, v33
	global_store_dwordx2 v[26:27], v[30:31], off offset:1024
	v_lshl_add_u64 v[26:27], v[26:27], 0, s[12:13]
	s_waitcnt vmcnt(7)
	v_lshlrev_b32_e32 v100, 16, v72
	v_and_b32_e32 v101, 0xffff0000, v72
	v_lshlrev_b32_e32 v102, 16, v78
	v_and_b32_e32 v103, 0xffff0000, v78
	v_lshlrev_b32_e32 v104, 16, v73
	v_and_b32_e32 v105, 0xffff0000, v73
	v_lshlrev_b32_e32 v106, 16, v79
	v_and_b32_e32 v107, 0xffff0000, v79
	v_pk_mul_f32 v[30:31], v[100:101], v[102:103]
	v_pk_mul_f32 v[32:33], v[104:105], v[106:107]
	v_lshlrev_b32_e32 v100, 16, v74
	v_and_b32_e32 v101, 0xffff0000, v74
	v_lshlrev_b32_e32 v102, 16, v80
	v_and_b32_e32 v103, 0xffff0000, v80
	v_lshlrev_b32_e32 v104, 16, v75
	v_and_b32_e32 v105, 0xffff0000, v75
	v_lshlrev_b32_e32 v106, 16, v81
	v_and_b32_e32 v107, 0xffff0000, v81
	v_pk_mul_f32 v[34:35], v[100:101], v[102:103]
	v_pk_mul_f32 v[36:37], v[104:105], v[106:107]
	v_lshlrev_b32_e32 v100, 16, v76
	v_and_b32_e32 v101, 0xffff0000, v76
	v_lshlrev_b32_e32 v102, 16, v82
	v_and_b32_e32 v103, 0xffff0000, v82
	v_lshlrev_b32_e32 v104, 16, v77
	v_and_b32_e32 v105, 0xffff0000, v77
	v_lshlrev_b32_e32 v106, 16, v83
	v_and_b32_e32 v107, 0xffff0000, v83
	v_pk_mul_f32 v[108:109], v[100:101], v[102:103]
	v_pk_mul_f32 v[110:111], v[104:105], v[106:107]
	v_pk_mul_f32 v[32:33], v[10:11], v[32:33]
	v_pk_mul_f32 v[30:31], v[8:9], v[30:31]
	v_pk_fma_f32 v[32:33], v[6:7], v[36:37], v[32:33]
	v_pk_fma_f32 v[30:31], v[4:5], v[34:35], v[30:31]
	v_pk_fma_f32 v[30:31], v[0:1], v[108:109], v[30:31]
	v_pk_fma_f32 v[32:33], v[2:3], v[110:111], v[32:33]
	v_lshlrev_b32_e32 v100, 16, v84
	v_and_b32_e32 v101, 0xffff0000, v84
	v_lshlrev_b32_e32 v102, 16, v85
	v_and_b32_e32 v103, 0xffff0000, v85
	v_pk_mul_f32 v[32:33], v[32:33], v[102:103]
	v_pk_mul_f32 v[30:31], v[30:31], v[100:101]
	v_cvt_pk_bf16_f32 v30, v30, v31
	v_cvt_pk_bf16_f32 v31, v32, v33
	global_store_dwordx2 v[26:27], v[30:31], off offset:1024
	v_lshl_add_u64 v[26:27], v[26:27], 0, s[12:13]
	s_waitcnt vmcnt(0)
	v_lshlrev_b32_e32 v100, 16, v86
	v_and_b32_e32 v101, 0xffff0000, v86
	v_lshlrev_b32_e32 v102, 16, v92
	v_and_b32_e32 v103, 0xffff0000, v92
	v_lshlrev_b32_e32 v104, 16, v87
	v_and_b32_e32 v105, 0xffff0000, v87
	v_lshlrev_b32_e32 v106, 16, v93
	v_and_b32_e32 v107, 0xffff0000, v93
	v_pk_mul_f32 v[30:31], v[100:101], v[102:103]
	v_pk_mul_f32 v[32:33], v[104:105], v[106:107]
	v_lshlrev_b32_e32 v100, 16, v88
	v_and_b32_e32 v101, 0xffff0000, v88
	v_lshlrev_b32_e32 v102, 16, v94
	v_and_b32_e32 v103, 0xffff0000, v94
	v_lshlrev_b32_e32 v104, 16, v89
	v_and_b32_e32 v105, 0xffff0000, v89
	v_lshlrev_b32_e32 v106, 16, v95
	v_and_b32_e32 v107, 0xffff0000, v95
	v_pk_mul_f32 v[34:35], v[100:101], v[102:103]
	v_pk_mul_f32 v[36:37], v[104:105], v[106:107]
	v_lshlrev_b32_e32 v100, 16, v90
	v_and_b32_e32 v101, 0xffff0000, v90
	v_lshlrev_b32_e32 v102, 16, v96
	v_and_b32_e32 v103, 0xffff0000, v96
	v_lshlrev_b32_e32 v104, 16, v91
	v_and_b32_e32 v105, 0xffff0000, v91
	v_lshlrev_b32_e32 v106, 16, v97
	v_and_b32_e32 v107, 0xffff0000, v97
	v_pk_mul_f32 v[108:109], v[100:101], v[102:103]
	v_pk_mul_f32 v[110:111], v[104:105], v[106:107]
	v_cmp_gt_i32_e32 vcc, s36, v28
	s_nop 1
	v_cndmask_b32_e32 v108, 0, v108, vcc
	v_cndmask_b32_e32 v109, 0, v109, vcc
	v_cndmask_b32_e32 v110, 0, v110, vcc
	v_cndmask_b32_e32 v111, 0, v111, vcc
	v_pk_mul_f32 v[32:33], v[10:11], v[32:33]
	v_pk_mul_f32 v[30:31], v[8:9], v[30:31]
	v_pk_fma_f32 v[32:33], v[6:7], v[36:37], v[32:33]
	v_pk_fma_f32 v[30:31], v[4:5], v[34:35], v[30:31]
	v_pk_fma_f32 v[30:31], v[0:1], v[108:109], v[30:31]
	v_pk_fma_f32 v[32:33], v[2:3], v[110:111], v[32:33]
	v_lshlrev_b32_e32 v100, 16, v98
	v_and_b32_e32 v101, 0xffff0000, v98
	v_lshlrev_b32_e32 v102, 16, v99
	v_and_b32_e32 v103, 0xffff0000, v99
	v_pk_mul_f32 v[32:33], v[32:33], v[102:103]
	v_pk_mul_f32 v[30:31], v[30:31], v[100:101]
	v_cvt_pk_bf16_f32 v30, v30, v31
	v_cvt_pk_bf16_f32 v31, v32, v33
	global_store_dwordx2 v[26:27], v[30:31], off offset:1024
	s_add_u32 s12, s4, 0xfea4400
	s_addc_u32 s13, s5, 0
	v_ashrrev_i32_e32 v42, 6, v40
	v_cmp_lt_i32_e32 vcc, 3, v42
	s_and_saveexec_b64 s[22:23], vcc
	s_xor_b64 s[22:23], exec, s[22:23]
	s_setprio 0
	s_andn2_saveexec_b64 s[22:23], s[22:23]
	s_setprio 2
	s_or_b64 exec, exec, s[22:23]
	v_and_b32_e32 v41, 15, v40
	v_lshl_or_b32 v0, v42, 4, v41
	s_add_i32 s24, s24, s25
	v_add_u32_e32 v104, s24, v0
	v_ashrrev_i32_e32 v105, 31, v104
	v_lshlrev_b64 v[0:1], 10, v[104:105]
	v_lshl_add_u64 v[0:1], s[4:5], 0, v[0:1]
	s_lshl_b32 s58, s35, 8
	v_lshl_add_u64 v[0:1], v[0:1], 0, s[58:59]
	v_and_b32_e32 v132, 48, v40
	v_lshl_add_u64 v[0:1], v[0:1], 0, v[132:133]
	s_mov_b64 s[4:5], 0xa2a4400
	v_lshl_add_u64 v[8:9], v[0:1], 0, s[4:5]
	s_mov_b32 s4, 0xa2a4000
	v_add_co_u32_e32 v10, vcc, s4, v0
	v_ashrrev_i32_e32 v36, 3, v40
	s_nop 0
	v_addc_co_u32_e32 v11, vcc, 0, v1, vcc
	global_load_dwordx4 v[0:3], v[8:9], off offset:64
	global_load_dwordx4 v[4:7], v[8:9], off offset:128
	global_load_dwordx4 v[12:15], v[10:11], off offset:1024
	s_nop 0
	global_load_dwordx4 v[8:11], v[8:9], off offset:192
	v_ashrrev_i32_e32 v37, 31, v36
	v_lshlrev_b64 v[34:35], 8, v[36:37]
	v_and_b32_e32 v37, 7, v40
	v_lshl_or_b32 v16, v37, 5, v34
	v_mov_b32_e32 v17, v35
	v_lshl_add_u64 v[32:33], s[18:19], 0, v[16:17]
	s_mov_b64 s[24:25], 0xc010
	v_and_b32_e32 v43, 63, v40
	v_bfe_u32 v105, v40, 4, 2
	s_lshl_b32 s22, s35, 7
	s_mov_b32 s4, 0
	s_lshr_b32 s23, s34, 6
	v_lshl_add_u64 v[38:39], v[32:33], 0, s[24:25]
	v_mov_b32_e32 v44, 0
